# FFN-up GEMM loop: LDS-DMA pieces issued between the MFMAs of the following compute cluster instead of in the load segment; counted waits 6/2
# baseline (speedup 1.0000x reference)
; #define PG8_STAGE(bufoff, gbase, voff) do { _Pragma("unroll") for (int _i = 0; _i < 2; ++_i) \
;         __builtin_amdgcn_global_load_lds((const unsigned*)((const char*)(gbase) + (voff)[_i]), (PG8_LAS unsigned*)(lds + (bufoff) + ldsw + _i * 8192), 16, 0, 0); } while (0)
; #define PG8_LDA(dst, b, h) do { _Pragma("unroll") for (int m = 0; m < 4; ++m) _Pragma("unroll") for (int k = 0; k < 2; ++k) dst[m][k] = *(const PG8_LAS bf16x8*)(lds + PG8_SA(b, h) + aoff + m * 2048 + k * 1024); } while (0)
; #define PG8_LDB(dst, b, h) do { _Pragma("unroll") for (int n = 0; n < 2; ++n) _Pragma("unroll") for (int k = 0; k < 2; ++k) dst[n][k] = *(const PG8_LAS bf16x8*)(lds + PG8_SB(b, h) + boff + n * 2048 + k * 1024); } while (0)
; #define PG8_MMA(ai, bj, At, Bt) do { __builtin_amdgcn_s_setprio(1); _Pragma("unroll") for (int m = 0; m < 4; ++m) _Pragma("unroll") for (int n = 0; n < 2; ++n) _Pragma("unroll") for (int k = 0; k < 2; ++k) \
;         acc[ai][bj][m][n] = mma16<Epi::F16A>(Bt[n][k], At[m][k], acc[ai][bj][m][n]); __builtin_amdgcn_s_setprio(0); } while (0)
; #define PG8_WAIT_V(n) asm volatile("s_waitcnt vmcnt(" #n ")" ::: "memory")
; #define PG8_WAIT_L(n) asm volatile("s_waitcnt lgkmcnt(" #n ")" ::: "memory")
; #define PG8_BAR __builtin_amdgcn_s_barrier()
; #define PG8_SCHED __builtin_amdgcn_sched_barrier(0)
; template <class Epi, class Sched, bool ALIGN_EPI = false, bool SP2 = false>
; __device__ __forceinline__ void gemm_phase(PG8_LAS unsigned char* lds, const Gemm g, const Sched& S, const Epi& E) {
;     ...
;             PG8_LDB(B0, 0, 0); PG8_LDB(B1, 0, 1); PG8_SCHED; PG8_LDA(At, 0, 0); PG8_STAGE(PG8_SA(1, 1), a1 + hstep, voffA);
;             PG8_WAIT_V(8); PG8_WAIT_L(0); PG8_BAR; PG8_MMA(0, 0, At, B0); PG8_MMA(0, 1, At, B1); PG8_BAR; PG8_SCHED;
;             PG8_LDA(At, 0, 1); PG8_STAGE(PG8_SB(0, 0), b2, voffB); PG8_STAGE(PG8_SB(0, 1), b2 + hstep, voffB); PG8_STAGE(PG8_SA(0, 0), a2, voffA);
;             PG8_WAIT_V(8); PG8_WAIT_L(0); PG8_BAR; PG8_MMA(1, 0, At, B0); PG8_MMA(1, 1, At, B1); PG8_BAR; PG8_SCHED;
.LBB0_1175:
	s_add_u32 s8, s0, 0xfffc0080
	s_addc_u32 s9, s1, -1
	s_add_i32 s88, 0, 0x10000
	s_cmp_eq_u32 s37, 12
	s_cselect_b32 s11, s27, s9
	s_cselect_b32 s10, vcc_lo, s8
	s_cselect_b32 s9, s25, s5
	s_cselect_b32 s8, vcc_hi, s4
	s_add_i32 s60, 0, 0x14000
	v_add_u32_e32 v142, s88, v208
	v_add_u32_e32 v154, s60, v208
	ds_read_b128 v[130:133], v142
	ds_read_b128 v[134:137], v142 offset:1024
	ds_read_b128 v[138:141], v142 offset:2048
	ds_read_b128 v[142:145], v142 offset:3072
	ds_read_b128 v[146:149], v154
	ds_read_b128 v[150:153], v154 offset:1024
	ds_read_b128 v[186:189], v154 offset:2048
	ds_read_b128 v[190:193], v154 offset:3072
	ds_read_b128 v[194:197], v209
	ds_read_b128 v[198:201], v209 offset:1024
	ds_read_b128 v[202:205], v209 offset:2048
	ds_read_b128 v[210:213], v209 offset:3072
	ds_read_b128 v[214:217], v209 offset:4096
	ds_read_b128 v[218:221], v209 offset:5120
	ds_read_b128 v[222:225], v209 offset:6144
	ds_read_b128 v[226:229], v209 offset:7168
	s_waitcnt vmcnt(6)
	s_waitcnt lgkmcnt(0)
	s_barrier
	s_setprio 1
	s_waitcnt lgkmcnt(0)
	v_mfma_f32_16x16x32_bf16 v[126:129], v[130:133], v[194:197], v[126:129]
	v_mfma_f32_16x16x32_bf16 v[122:125], v[138:141], v[194:197], v[122:125]
	v_mfma_f32_16x16x32_bf16 v[106:109], v[130:133], v[202:205], v[106:109]
	v_mfma_f32_16x16x32_bf16 v[78:81], v[138:141], v[202:205], v[78:81]
	v_mfma_f32_16x16x32_bf16 v[102:105], v[130:133], v[214:217], v[102:105]
	v_mfma_f32_16x16x32_bf16 v[74:77], v[138:141], v[214:217], v[74:77]
	v_mfma_f32_16x16x32_bf16 v[118:121], v[130:133], v[222:225], v[118:121]
	v_mfma_f32_16x16x32_bf16 v[110:113], v[138:141], v[222:225], v[110:113]
	v_mfma_f32_16x16x32_bf16 v[126:129], v[134:137], v[198:201], v[126:129]
	v_lshl_add_u64 v[154:155], s[0:1], 0, v[182:183]
	s_add_i32 m0, s54, 0xc000
	s_nop 0
	global_load_lds_dwordx4 v[154:155], off
	v_mfma_f32_16x16x32_bf16 v[122:125], v[142:145], v[198:201], v[122:125]
	v_mfma_f32_16x16x32_bf16 v[106:109], v[134:137], v[210:213], v[106:109]
	v_mfma_f32_16x16x32_bf16 v[78:81], v[142:145], v[210:213], v[78:81]
	v_mfma_f32_16x16x32_bf16 v[102:105], v[134:137], v[218:221], v[102:105]
	v_mfma_f32_16x16x32_bf16 v[74:77], v[142:145], v[218:221], v[74:77]
	v_mfma_f32_16x16x32_bf16 v[118:121], v[134:137], v[226:229], v[118:121]
	v_mfma_f32_16x16x32_bf16 v[110:113], v[142:145], v[226:229], v[110:113]
	s_setprio 0
	s_setprio 1
	v_mfma_f32_16x16x32_bf16 v[86:89], v[146:149], v[194:197], v[86:89]
	v_mfma_f32_16x16x32_bf16 v[58:61], v[186:189], v[194:197], v[58:61]
	v_mfma_f32_16x16x32_bf16 v[42:45], v[146:149], v[202:205], v[42:45]
	v_mfma_f32_16x16x32_bf16 v[18:21], v[186:189], v[202:205], v[18:21]
	v_mfma_f32_16x16x32_bf16 v[38:41], v[146:149], v[214:217], v[38:41]
	v_mfma_f32_16x16x32_bf16 v[14:17], v[186:189], v[214:217], v[14:17]
	v_mfma_f32_16x16x32_bf16 v[98:101], v[146:149], v[222:225], v[98:101]
	v_mfma_f32_16x16x32_bf16 v[70:73], v[186:189], v[222:225], v[70:73]
	v_mfma_f32_16x16x32_bf16 v[86:89], v[150:153], v[198:201], v[86:89]
	v_lshl_add_u64 v[154:155], s[0:1], 0, v[184:185]
	s_add_i32 m0, s54, 0xe000
	s_nop 0
	global_load_lds_dwordx4 v[154:155], off
	v_mfma_f32_16x16x32_bf16 v[58:61], v[190:193], v[198:201], v[58:61]
	v_mfma_f32_16x16x32_bf16 v[42:45], v[150:153], v[210:213], v[42:45]
	v_mfma_f32_16x16x32_bf16 v[18:21], v[190:193], v[210:213], v[18:21]
	v_mfma_f32_16x16x32_bf16 v[38:41], v[150:153], v[218:221], v[38:41]
	v_mfma_f32_16x16x32_bf16 v[14:17], v[190:193], v[218:221], v[14:17]
	v_mfma_f32_16x16x32_bf16 v[98:101], v[150:153], v[226:229], v[98:101]
	v_mfma_f32_16x16x32_bf16 v[70:73], v[190:193], v[226:229], v[70:73]
	s_setprio 0
	s_barrier
	ds_read_b128 v[194:197], v209 offset:16384
	ds_read_b128 v[198:201], v209 offset:17408
	ds_read_b128 v[202:205], v209 offset:18432
	ds_read_b128 v[210:213], v209 offset:19456
	ds_read_b128 v[214:217], v209 offset:20480
	ds_read_b128 v[218:221], v209 offset:21504
	ds_read_b128 v[222:225], v209 offset:22528
	ds_read_b128 v[226:229], v209 offset:23552
	s_waitcnt vmcnt(2)
	s_waitcnt lgkmcnt(0)
	s_barrier
	s_setprio 1
	s_waitcnt lgkmcnt(0)
	v_mfma_f32_16x16x32_bf16 v[94:97], v[130:133], v[194:197], v[94:97]
	v_mfma_f32_16x16x32_bf16 v[66:69], v[138:141], v[194:197], v[66:69]
	v_mfma_f32_16x16x32_bf16 v[90:93], v[130:133], v[202:205], v[90:93]
	s_add_i32 s88, s88, s28
	v_lshl_add_u64 v[154:155], s[8:9], 0, v[0:1]
	s_mov_b32 m0, s88
	s_nop 0
	global_load_lds_dwordx4 v[154:155], off
	v_mfma_f32_16x16x32_bf16 v[62:65], v[138:141], v[202:205], v[62:65]
	v_mfma_f32_16x16x32_bf16 v[46:49], v[130:133], v[214:217], v[46:49]
	v_mfma_f32_16x16x32_bf16 v[54:57], v[138:141], v[214:217], v[54:57]
	v_mfma_f32_16x16x32_bf16 v[114:117], v[130:133], v[222:225], v[114:117]
	v_mfma_f32_16x16x32_bf16 v[82:85], v[138:141], v[222:225], v[82:85]
	v_mfma_f32_16x16x32_bf16 v[94:97], v[134:137], v[198:201], v[94:97]
	s_add_i32 m0, s88, 0x2000
	s_add_u32 s88, s8, 0x40000
	v_lshl_add_u64 v[162:163], s[8:9], 0, v[156:157]
	s_addc_u32 s89, s9, 0
	s_add_i32 s60, s60, s28
	global_load_lds_dwordx4 v[162:163], off
	v_mfma_f32_16x16x32_bf16 v[66:69], v[142:145], v[198:201], v[66:69]
	v_mfma_f32_16x16x32_bf16 v[90:93], v[134:137], v[210:213], v[90:93]
	v_mfma_f32_16x16x32_bf16 v[62:65], v[142:145], v[210:213], v[62:65]
	v_mfma_f32_16x16x32_bf16 v[46:49], v[134:137], v[218:221], v[46:49]
	v_mfma_f32_16x16x32_bf16 v[54:57], v[142:145], v[218:221], v[54:57]
	v_lshl_add_u64 v[230:231], s[88:89], 0, v[0:1]
	s_mov_b32 m0, s60
	v_lshl_add_u64 v[234:235], s[10:11], 0, v[158:159]
	global_load_lds_dwordx4 v[230:231], off
	v_mfma_f32_16x16x32_bf16 v[114:117], v[134:137], v[226:229], v[114:117]
	v_mfma_f32_16x16x32_bf16 v[82:85], v[142:145], v[226:229], v[82:85]
; #define PG8_STAGE(bufoff, gbase, voff) do { _Pragma("unroll") for (int _i = 0; _i < 2; ++_i) \
;         __builtin_amdgcn_global_load_lds((const unsigned*)((const char*)(gbase) + (voff)[_i]), (PG8_LAS unsigned*)(lds + (bufoff) + ldsw + _i * 8192), 16, 0, 0); } while (0)
; #define PG8_LDA(dst, b, h) do { _Pragma("unroll") for (int m = 0; m < 4; ++m) _Pragma("unroll") for (int k = 0; k < 2; ++k) dst[m][k] = *(const PG8_LAS bf16x8*)(lds + PG8_SA(b, h) + aoff + m * 2048 + k * 1024); } while (0)
; #define PG8_LDB(dst, b, h) do { _Pragma("unroll") for (int n = 0; n < 2; ++n) _Pragma("unroll") for (int k = 0; k < 2; ++k) dst[n][k] = *(const PG8_LAS bf16x8*)(lds + PG8_SB(b, h) + boff + n * 2048 + k * 1024); } while (0)
; #define PG8_MMA(ai, bj, At, Bt) do { __builtin_amdgcn_s_setprio(1); _Pragma("unroll") for (int m = 0; m < 4; ++m) _Pragma("unroll") for (int n = 0; n < 2; ++n) _Pragma("unroll") for (int k = 0; k < 2; ++k) \
;         acc[ai][bj][m][n] = mma16<Epi::F16A>(Bt[n][k], At[m][k], acc[ai][bj][m][n]); __builtin_amdgcn_s_setprio(0); } while (0)
; #define PG8_WAIT_V(n) asm volatile("s_waitcnt vmcnt(" #n ")" ::: "memory")
; #define PG8_WAIT_L(n) asm volatile("s_waitcnt lgkmcnt(" #n ")" ::: "memory")
; #define PG8_BAR __builtin_amdgcn_s_barrier()
; #define PG8_SCHED __builtin_amdgcn_sched_barrier(0)
; template <class Epi, class Sched, bool ALIGN_EPI = false, bool SP2 = false>
; __device__ __forceinline__ void gemm_phase(PG8_LAS unsigned char* lds, const Gemm g, const Sched& S, const Epi& E) {
;     ...
;             PG8_WAIT_V(8); PG8_WAIT_L(0); PG8_BAR; PG8_MMA(1, 0, At, B0); PG8_MMA(1, 1, At, B1); PG8_BAR; PG8_SCHED;
;             PG8_LDB(B0, 1, 0); PG8_LDB(B1, 1, 1); PG8_SCHED; PG8_LDA(At, 1, 0); PG8_STAGE(PG8_SA(0, 1), a2 + hstep, voffA);
;             PG8_WAIT_V(8); PG8_WAIT_L(0); PG8_BAR; PG8_MMA(0, 0, At, B0); PG8_MMA(0, 1, At, B1); PG8_BAR; PG8_SCHED;
	s_setprio 0
	s_setprio 1
	v_mfma_f32_16x16x32_bf16 v[34:37], v[146:149], v[194:197], v[34:37]
	v_mfma_f32_16x16x32_bf16 v[10:13], v[186:189], v[194:197], v[10:13]
	v_mfma_f32_16x16x32_bf16 v[26:29], v[146:149], v[202:205], v[26:29]
	v_lshl_add_u64 v[230:231], s[88:89], 0, v[156:157]
	s_add_i32 m0, s60, 0x2000
	s_nop 0
	global_load_lds_dwordx4 v[230:231], off
	v_mfma_f32_16x16x32_bf16 v[6:9], v[186:189], v[202:205], v[6:9]
	v_mfma_f32_16x16x32_bf16 v[22:25], v[146:149], v[214:217], v[22:25]
	v_mfma_f32_16x16x32_bf16 v[2:5], v[186:189], v[214:217], v[2:5]
	v_mfma_f32_16x16x32_bf16 v[50:53], v[146:149], v[222:225], v[50:53]
	v_mfma_f32_16x16x32_bf16 v[30:33], v[186:189], v[222:225], v[30:33]
	v_mfma_f32_16x16x32_bf16 v[34:37], v[150:153], v[198:201], v[34:37]
	v_lshl_add_u64 v[230:231], s[10:11], 0, v[160:161]
	s_mov_b32 m0, s54
	s_nop 0
	global_load_lds_dwordx4 v[230:231], off
	v_mfma_f32_16x16x32_bf16 v[10:13], v[190:193], v[198:201], v[10:13]
	v_mfma_f32_16x16x32_bf16 v[26:29], v[150:153], v[210:213], v[26:29]
	v_mfma_f32_16x16x32_bf16 v[6:9], v[190:193], v[210:213], v[6:9]
	v_mfma_f32_16x16x32_bf16 v[22:25], v[150:153], v[218:221], v[22:25]
	v_mfma_f32_16x16x32_bf16 v[2:5], v[190:193], v[218:221], v[2:5]
	s_mov_b32 m0, s55
	s_nop 0
	global_load_lds_dwordx4 v[234:235], off
	v_mfma_f32_16x16x32_bf16 v[50:53], v[150:153], v[226:229], v[50:53]
	v_mfma_f32_16x16x32_bf16 v[30:33], v[190:193], v[226:229], v[30:33]
	s_setprio 0
	s_barrier
	s_add_i32 s60, 0, 0x18000
	s_add_i32 s88, 0, 0x1c000
	v_add_u32_e32 v142, s60, v208
	v_add_u32_e32 v190, s88, v208
	ds_read_b128 v[130:133], v142
	ds_read_b128 v[134:137], v142 offset:1024
	ds_read_b128 v[138:141], v142 offset:2048
	ds_read_b128 v[142:145], v142 offset:3072
	ds_read_b128 v[146:149], v190
	ds_read_b128 v[150:153], v190 offset:1024
	ds_read_b128 v[186:189], v190 offset:2048
	ds_read_b128 v[190:193], v190 offset:3072
	ds_read_b128 v[194:197], v209 offset:32768
	ds_read_b128 v[198:201], v209 offset:33792
	ds_read_b128 v[202:205], v209 offset:34816
	ds_read_b128 v[210:213], v209 offset:35840
	ds_read_b128 v[214:217], v209 offset:36864
	ds_read_b128 v[218:221], v209 offset:37888
	ds_read_b128 v[222:225], v209 offset:38912
	ds_read_b128 v[226:229], v209 offset:39936
	s_waitcnt vmcnt(6)
	s_waitcnt lgkmcnt(0)
	s_barrier
	s_setprio 1
	s_waitcnt lgkmcnt(0)
	v_mfma_f32_16x16x32_bf16 v[126:129], v[130:133], v[194:197], v[126:129]
	v_mfma_f32_16x16x32_bf16 v[122:125], v[138:141], v[194:197], v[122:125]
	v_mfma_f32_16x16x32_bf16 v[106:109], v[130:133], v[202:205], v[106:109]
	v_mfma_f32_16x16x32_bf16 v[78:81], v[138:141], v[202:205], v[78:81]
	v_mfma_f32_16x16x32_bf16 v[102:105], v[130:133], v[214:217], v[102:105]
	v_mfma_f32_16x16x32_bf16 v[74:77], v[138:141], v[214:217], v[74:77]
	v_mfma_f32_16x16x32_bf16 v[118:121], v[130:133], v[222:225], v[118:121]
	v_mfma_f32_16x16x32_bf16 v[110:113], v[138:141], v[222:225], v[110:113]
	v_mfma_f32_16x16x32_bf16 v[126:129], v[134:137], v[198:201], v[126:129]
	s_add_u32 s10, s10, 0x40000
	s_addc_u32 s11, s11, 0
	s_mov_b32 m0, s57
	v_lshl_add_u64 v[236:237], s[10:11], 0, v[160:161]
	global_load_lds_dwordx4 v[236:237], off
	v_mfma_f32_16x16x32_bf16 v[122:125], v[142:145], v[198:201], v[122:125]
	v_mfma_f32_16x16x32_bf16 v[106:109], v[134:137], v[210:213], v[106:109]
	v_mfma_f32_16x16x32_bf16 v[78:81], v[142:145], v[210:213], v[78:81]
	v_mfma_f32_16x16x32_bf16 v[102:105], v[134:137], v[218:221], v[102:105]
	v_mfma_f32_16x16x32_bf16 v[74:77], v[142:145], v[218:221], v[74:77]
	v_mfma_f32_16x16x32_bf16 v[118:121], v[134:137], v[226:229], v[118:121]
	v_mfma_f32_16x16x32_bf16 v[110:113], v[142:145], v[226:229], v[110:113]
	s_setprio 0
	s_setprio 1
	v_mfma_f32_16x16x32_bf16 v[86:89], v[146:149], v[194:197], v[86:89]
	v_mfma_f32_16x16x32_bf16 v[58:61], v[186:189], v[194:197], v[58:61]
	v_mfma_f32_16x16x32_bf16 v[42:45], v[146:149], v[202:205], v[42:45]
	v_mfma_f32_16x16x32_bf16 v[18:21], v[186:189], v[202:205], v[18:21]
	v_mfma_f32_16x16x32_bf16 v[38:41], v[146:149], v[214:217], v[38:41]
	v_mfma_f32_16x16x32_bf16 v[14:17], v[186:189], v[214:217], v[14:17]
	v_mfma_f32_16x16x32_bf16 v[98:101], v[146:149], v[222:225], v[98:101]
	v_mfma_f32_16x16x32_bf16 v[70:73], v[186:189], v[222:225], v[70:73]
	v_mfma_f32_16x16x32_bf16 v[86:89], v[150:153], v[198:201], v[86:89]
	v_lshl_add_u64 v[236:237], s[10:11], 0, v[158:159]
	s_mov_b32 m0, s59
	s_nop 0
	global_load_lds_dwordx4 v[236:237], off
	v_mfma_f32_16x16x32_bf16 v[58:61], v[190:193], v[198:201], v[58:61]
	v_mfma_f32_16x16x32_bf16 v[42:45], v[150:153], v[210:213], v[42:45]
	v_mfma_f32_16x16x32_bf16 v[18:21], v[190:193], v[210:213], v[18:21]
	v_mfma_f32_16x16x32_bf16 v[38:41], v[150:153], v[218:221], v[38:41]
	v_mfma_f32_16x16x32_bf16 v[14:17], v[190:193], v[218:221], v[14:17]
	v_mfma_f32_16x16x32_bf16 v[98:101], v[150:153], v[226:229], v[98:101]
	v_mfma_f32_16x16x32_bf16 v[70:73], v[190:193], v[226:229], v[70:73]
	s_setprio 0
	s_barrier
; #define PG8_STAGE(bufoff, gbase, voff) do { _Pragma("unroll") for (int _i = 0; _i < 2; ++_i) \
;         __builtin_amdgcn_global_load_lds((const unsigned*)((const char*)(gbase) + (voff)[_i]), (PG8_LAS unsigned*)(lds + (bufoff) + ldsw + _i * 8192), 16, 0, 0); } while (0)
; #define PG8_LDA(dst, b, h) do { _Pragma("unroll") for (int m = 0; m < 4; ++m) _Pragma("unroll") for (int k = 0; k < 2; ++k) dst[m][k] = *(const PG8_LAS bf16x8*)(lds + PG8_SA(b, h) + aoff + m * 2048 + k * 1024); } while (0)
; #define PG8_MMA(ai, bj, At, Bt) do { __builtin_amdgcn_s_setprio(1); _Pragma("unroll") for (int m = 0; m < 4; ++m) _Pragma("unroll") for (int n = 0; n < 2; ++n) _Pragma("unroll") for (int k = 0; k < 2; ++k) \
;         acc[ai][bj][m][n] = mma16<Epi::F16A>(Bt[n][k], At[m][k], acc[ai][bj][m][n]); __builtin_amdgcn_s_setprio(0); } while (0)
; #define PG8_WAIT_V(n) asm volatile("s_waitcnt vmcnt(" #n ")" ::: "memory")
; #define PG8_WAIT_L(n) asm volatile("s_waitcnt lgkmcnt(" #n ")" ::: "memory")
; #define PG8_BAR __builtin_amdgcn_s_barrier()
; #define PG8_SCHED __builtin_amdgcn_sched_barrier(0)
; template <class Epi, class Sched, bool ALIGN_EPI = false, bool SP2 = false>
; __device__ __forceinline__ void gemm_phase(PG8_LAS unsigned char* lds, const Gemm g, const Sched& S, const Epi& E) {
;     ...
;         for (int t = 0; t < nt; t += 2) {
;             const bool last = (t == nt - 2);
;     ...
;             PG8_LDA(At, 1, 1); PG8_STAGE(PG8_SB(1, 0), b3, voffB); PG8_STAGE(PG8_SB(1, 1), b3 + hstep, voffB); PG8_STAGE(PG8_SA(1, 0), a3, voffA);
;             PG8_WAIT_V(8); PG8_WAIT_L(0); PG8_BAR; PG8_MMA(1, 0, At, B0); PG8_MMA(1, 1, At, B1); PG8_BAR; PG8_SCHED;
	ds_read_b128 v[194:197], v209 offset:49152
	ds_read_b128 v[198:201], v209 offset:50176
	ds_read_b128 v[202:205], v209 offset:51200
	ds_read_b128 v[210:213], v209 offset:52224
	ds_read_b128 v[214:217], v209 offset:53248
	ds_read_b128 v[218:221], v209 offset:54272
	ds_read_b128 v[222:225], v209 offset:55296
	ds_read_b128 v[226:229], v209 offset:56320
	s_waitcnt vmcnt(2)
	s_waitcnt lgkmcnt(0)
	s_barrier
	s_setprio 1
	s_waitcnt lgkmcnt(0)
	v_mfma_f32_16x16x32_bf16 v[94:97], v[130:133], v[194:197], v[94:97]
	v_mfma_f32_16x16x32_bf16 v[66:69], v[138:141], v[194:197], v[66:69]
	v_mfma_f32_16x16x32_bf16 v[90:93], v[130:133], v[202:205], v[90:93]
	s_add_i32 s10, s60, s28
	v_lshl_add_u64 v[154:155], v[154:155], 0, s[92:93]
	s_mov_b32 m0, s10
	s_nop 0
	global_load_lds_dwordx4 v[154:155], off
	v_mfma_f32_16x16x32_bf16 v[62:65], v[138:141], v[202:205], v[62:65]
	v_mfma_f32_16x16x32_bf16 v[46:49], v[130:133], v[214:217], v[46:49]
	v_mfma_f32_16x16x32_bf16 v[54:57], v[138:141], v[214:217], v[54:57]
	v_mfma_f32_16x16x32_bf16 v[114:117], v[130:133], v[222:225], v[114:117]
	v_mfma_f32_16x16x32_bf16 v[82:85], v[138:141], v[222:225], v[82:85]
	v_mfma_f32_16x16x32_bf16 v[94:97], v[134:137], v[198:201], v[94:97]
	s_add_i32 m0, s10, 0x2000
	s_add_u32 s8, s8, 0x40080
	v_lshl_add_u64 v[154:155], v[162:163], 0, s[92:93]
	s_addc_u32 s9, s9, 0
	s_add_i32 s10, s88, s28
	global_load_lds_dwordx4 v[154:155], off
	v_mfma_f32_16x16x32_bf16 v[66:69], v[142:145], v[198:201], v[66:69]
	v_mfma_f32_16x16x32_bf16 v[90:93], v[134:137], v[210:213], v[90:93]
	v_mfma_f32_16x16x32_bf16 v[62:65], v[142:145], v[210:213], v[62:65]
	v_mfma_f32_16x16x32_bf16 v[46:49], v[134:137], v[218:221], v[46:49]
	v_mfma_f32_16x16x32_bf16 v[54:57], v[142:145], v[218:221], v[54:57]
	v_lshl_add_u64 v[154:155], s[8:9], 0, v[0:1]
	s_mov_b32 m0, s10
	s_nop 0
	global_load_lds_dwordx4 v[154:155], off
	v_mfma_f32_16x16x32_bf16 v[114:117], v[134:137], v[226:229], v[114:117]
	v_mfma_f32_16x16x32_bf16 v[82:85], v[142:145], v[226:229], v[82:85]
	s_setprio 0
	s_setprio 1
	v_mfma_f32_16x16x32_bf16 v[34:37], v[146:149], v[194:197], v[34:37]
	v_mfma_f32_16x16x32_bf16 v[10:13], v[186:189], v[194:197], v[10:13]
	v_mfma_f32_16x16x32_bf16 v[26:29], v[146:149], v[202:205], v[26:29]
	v_lshl_add_u64 v[154:155], s[8:9], 0, v[156:157]
	s_add_i32 m0, s10, 0x2000
	s_nop 0
	global_load_lds_dwordx4 v[154:155], off
	v_mfma_f32_16x16x32_bf16 v[6:9], v[186:189], v[202:205], v[6:9]
	v_mfma_f32_16x16x32_bf16 v[22:25], v[146:149], v[214:217], v[22:25]
	v_mfma_f32_16x16x32_bf16 v[2:5], v[186:189], v[214:217], v[2:5]
	v_mfma_f32_16x16x32_bf16 v[50:53], v[146:149], v[222:225], v[50:53]
	v_mfma_f32_16x16x32_bf16 v[30:33], v[186:189], v[222:225], v[30:33]
	v_mfma_f32_16x16x32_bf16 v[34:37], v[150:153], v[198:201], v[34:37]
	v_lshl_add_u64 v[154:155], v[230:231], 0, s[92:93]
	s_mov_b32 m0, s70
	s_nop 0
	global_load_lds_dwordx4 v[154:155], off
	v_mfma_f32_16x16x32_bf16 v[10:13], v[190:193], v[198:201], v[10:13]
	v_mfma_f32_16x16x32_bf16 v[26:29], v[150:153], v[210:213], v[26:29]
	v_mfma_f32_16x16x32_bf16 v[6:9], v[190:193], v[210:213], v[6:9]
	v_mfma_f32_16x16x32_bf16 v[22:25], v[150:153], v[218:221], v[22:25]
	v_mfma_f32_16x16x32_bf16 v[2:5], v[190:193], v[218:221], v[2:5]
	v_lshl_add_u64 v[154:155], v[234:235], 0, s[92:93]
	s_mov_b32 m0, s71
	s_nop 0
	global_load_lds_dwordx4 v[154:155], off
	v_mfma_f32_16x16x32_bf16 v[50:53], v[150:153], v[226:229], v[50:53]
	v_mfma_f32_16x16x32_bf16 v[30:33], v[190:193], v[226:229], v[30:33]
	s_setprio 0
	s_barrier
	s_add_i32 s37, s37, 2
	s_add_u32 s0, s0, 0x100
	s_addc_u32 s1, s1, 0
	s_add_u32 s4, s4, 0x100
	s_addc_u32 s5, s5, 0
	s_cmp_gt_u32 s37, 13
	s_cbranch_scc0 .LBB0_1175
	s_and_b64 vcc, exec, s[50:51]
	s_cbranch_vccz .LBB0_1178
	s_barrier
